# speedup vs baseline: 1.0020x; 1.0020x over previous
; __device__ __forceinline__ unsigned pk2(float lo, float hi) { hwf2 v = {lo, hi}; return __builtin_bit_cast(unsigned, __builtin_convertvector(v, hwbf2)); }
; template <int EPI> ...
;     ...
;       if (vrow < 0) {
;         const int coff = (fq & 1) ? 16 + (fq - 1) * 4 : fq * 4;
;         _Pragma("unroll") for (int ai = 0; ai < 2; ++ai) _Pragma("unroll") for (int m = 0; m < 4; ++m) _Pragma("unroll") for (int bj = 0; bj < 2; ++bj) {
;           uint2 a, b;
;           a.x = pk2(acc[ai][bj][m][0][0], acc[ai][bj][m][0][1]); a.y = pk2(acc[ai][bj][m][0][2], acc[ai][bj][m][0][3]);
;           b.x = pk2(acc[ai][bj][m][1][0], acc[ai][bj][m][1][1]); b.y = pk2(acc[ai][bj][m][1][2], acc[ai][bj][m][1][3]);
;           *(uint4*)(proj + (size_t)(brow + ai * HALF + wr * 64 + m * 16 + fr) * NPROJ + (bcol + bj * HALF + wc * 32 + coff)) = widen_pair(a, b);
;         }
.LBB0_143:
	s_andn2_b64 vcc, exec, s[20:21]
	s_cbranch_vccnz .LBB0_108
	v_and_b32_e32 v0, 16, v175
	v_lshlrev_b32_e32 v10, 2, v17
	v_add_u32_e32 v11, 12, v10
	v_cmp_eq_u32_e32 vcc, 0, v0
	s_waitcnt lgkmcnt(0)
	v_cvt_pk_bf16_f32 v12, v148, v149
	v_cvt_pk_bf16_f32 v13, v144, v145
	v_cndmask_b32_e32 v0, v11, v10, vcc
	v_or_b32_e32 v10, s14, v15
	v_lshl_add_u32 v76, v14, 6, v10
	v_or3_b32 v14, v0, v16, s15
	v_mov_b64_e32 v[16:17], s[8:9]
	v_ashrrev_i32_e32 v15, 31, v14
	v_mad_i64_i32 v[74:75], s[14:15], v76, s57, v[16:17]
	v_cvt_pk_bf16_f32 v10, v142, v143
	v_cvt_pk_bf16_f32 v11, v136, v137
	v_lshlrev_b64 v[14:15], 1, v[14:15]
	v_permlane16_swap_b32_e32 v10, v12
	v_permlane16_swap_b32_e32 v11, v13
	v_lshl_add_u64 v[74:75], v[74:75], 0, v[14:15]
	global_store_dwordx4 v[74:75], v[10:13], off nt
	v_or_b32_e32 v0, 16, v76
	s_nop 0
	v_cvt_pk_bf16_f32 v10, v138, v139
	v_cvt_pk_bf16_f32 v11, v114, v115
	v_cvt_pk_bf16_f32 v12, v140, v141
	v_cvt_pk_bf16_f32 v13, v134, v135
	s_nop 0
	v_permlane16_swap_b32_e32 v10, v12
	v_permlane16_swap_b32_e32 v11, v13
	global_store_dwordx4 v[74:75], v[10:13], off offset:256 nt
	v_mad_i64_i32 v[74:75], s[14:15], v0, s57, v[16:17]
	s_nop 0
	v_cvt_pk_bf16_f32 v10, v118, v119
	v_cvt_pk_bf16_f32 v11, v116, v117
	v_cvt_pk_bf16_f32 v12, v124, v125
	v_cvt_pk_bf16_f32 v13, v120, v121
	s_nop 0
	v_permlane16_swap_b32_e32 v10, v12
	v_permlane16_swap_b32_e32 v11, v13
	v_lshl_add_u64 v[74:75], v[74:75], 0, v[14:15]
	global_store_dwordx4 v[74:75], v[10:13], off nt
	v_or_b32_e32 v0, 32, v76
	s_nop 0
	v_cvt_pk_bf16_f32 v10, v126, v127
	v_cvt_pk_bf16_f32 v11, v98, v99
	v_cvt_pk_bf16_f32 v12, v128, v129
	v_cvt_pk_bf16_f32 v13, v122, v123
	s_nop 0
	v_permlane16_swap_b32_e32 v10, v12
	v_permlane16_swap_b32_e32 v11, v13
	global_store_dwordx4 v[74:75], v[10:13], off offset:256 nt
	v_mad_i64_i32 v[74:75], s[14:15], v0, s57, v[16:17]
	s_nop 0
	v_cvt_pk_bf16_f32 v10, v102, v103
	v_cvt_pk_bf16_f32 v11, v100, v101
	v_cvt_pk_bf16_f32 v12, v108, v109
	v_cvt_pk_bf16_f32 v13, v104, v105
	s_nop 0
	v_permlane16_swap_b32_e32 v10, v12
	v_permlane16_swap_b32_e32 v11, v13
	v_lshl_add_u64 v[74:75], v[74:75], 0, v[14:15]
	global_store_dwordx4 v[74:75], v[10:13], off nt
	v_or_b32_e32 v0, 48, v76
	s_nop 0
	v_cvt_pk_bf16_f32 v10, v110, v111
	v_cvt_pk_bf16_f32 v11, v82, v83
	v_cvt_pk_bf16_f32 v12, v112, v113
	v_cvt_pk_bf16_f32 v13, v106, v107
	s_nop 0
	v_permlane16_swap_b32_e32 v10, v12
	v_permlane16_swap_b32_e32 v11, v13
	global_store_dwordx4 v[74:75], v[10:13], off offset:256 nt
	v_mad_i64_i32 v[74:75], s[14:15], v0, s57, v[16:17]
	s_nop 0
	v_cvt_pk_bf16_f32 v10, v86, v87
	v_cvt_pk_bf16_f32 v11, v84, v85
	v_cvt_pk_bf16_f32 v12, v92, v93
	v_cvt_pk_bf16_f32 v13, v88, v89
	s_nop 0
	v_permlane16_swap_b32_e32 v10, v12
	v_permlane16_swap_b32_e32 v11, v13
	v_lshl_add_u64 v[74:75], v[74:75], 0, v[14:15]
	global_store_dwordx4 v[74:75], v[10:13], off nt
	v_add_u32_e32 v0, 0x80, v76
	s_nop 0
	v_cvt_pk_bf16_f32 v10, v94, v95
	v_cvt_pk_bf16_f32 v11, v52, v53
	v_cvt_pk_bf16_f32 v12, v96, v97
	v_cvt_pk_bf16_f32 v13, v90, v91
	s_nop 0
	v_permlane16_swap_b32_e32 v10, v12
	v_permlane16_swap_b32_e32 v11, v13
	global_store_dwordx4 v[74:75], v[10:13], off offset:256 nt
	v_mad_i64_i32 v[52:53], s[14:15], v0, s57, v[16:17]
	s_nop 0
	v_cvt_pk_bf16_f32 v10, v64, v65
	v_cvt_pk_bf16_f32 v11, v58, v59
	v_cvt_pk_bf16_f32 v12, v78, v79
	v_cvt_pk_bf16_f32 v13, v68, v69
	s_nop 0
	v_permlane16_swap_b32_e32 v10, v12
	v_permlane16_swap_b32_e32 v11, v13
	v_lshl_add_u64 v[52:53], v[52:53], 0, v[14:15]
	global_store_dwordx4 v[52:53], v[10:13], off nt
	v_add_u32_e32 v0, 0x90, v76
	s_nop 0
	v_cvt_pk_bf16_f32 v10, v70, v71
	v_cvt_pk_bf16_f32 v11, v50, v51
	v_cvt_pk_bf16_f32 v12, v72, v73
	v_cvt_pk_bf16_f32 v13, v66, v67
	s_nop 0
	v_permlane16_swap_b32_e32 v10, v12
	v_permlane16_swap_b32_e32 v11, v13
	global_store_dwordx4 v[52:53], v[10:13], off offset:256 nt
	v_mad_i64_i32 v[50:51], s[14:15], v0, s57, v[16:17]
	s_nop 0
	v_cvt_pk_bf16_f32 v10, v46, v47
	v_cvt_pk_bf16_f32 v11, v48, v49
	v_cvt_pk_bf16_f32 v12, v56, v57
	v_cvt_pk_bf16_f32 v13, v54, v55
	s_nop 0
	v_permlane16_swap_b32_e32 v10, v12
	v_permlane16_swap_b32_e32 v11, v13
	v_lshl_add_u64 v[46:47], v[50:51], 0, v[14:15]
	global_store_dwordx4 v[46:47], v[10:13], off nt
	v_add_u32_e32 v0, 0xa0, v76
	s_nop 0
	v_cvt_pk_bf16_f32 v10, v60, v61
	v_cvt_pk_bf16_f32 v11, v34, v35
	v_cvt_pk_bf16_f32 v12, v62, v63
	v_cvt_pk_bf16_f32 v13, v44, v45
	s_nop 0
	v_permlane16_swap_b32_e32 v10, v12
	v_permlane16_swap_b32_e32 v11, v13
	global_store_dwordx4 v[46:47], v[10:13], off offset:256 nt
	v_mad_i64_i32 v[34:35], s[14:15], v0, s57, v[16:17]
	s_nop 0
	v_cvt_pk_bf16_f32 v10, v30, v31
	v_cvt_pk_bf16_f32 v11, v32, v33
	v_cvt_pk_bf16_f32 v12, v38, v39
	v_cvt_pk_bf16_f32 v13, v36, v37
	s_nop 0
	v_permlane16_swap_b32_e32 v10, v12
	v_permlane16_swap_b32_e32 v11, v13
	v_lshl_add_u64 v[30:31], v[34:35], 0, v[14:15]
	global_store_dwordx4 v[30:31], v[10:13], off nt
	v_add_u32_e32 v0, 0xb0, v76
	v_mad_i64_i32 v[16:17], s[14:15], v0, s57, v[16:17]
	v_cvt_pk_bf16_f32 v10, v40, v41
	v_cvt_pk_bf16_f32 v11, v18, v19
	v_cvt_pk_bf16_f32 v12, v42, v43
	v_cvt_pk_bf16_f32 v13, v28, v29
	s_nop 0
	v_permlane16_swap_b32_e32 v10, v12
	v_permlane16_swap_b32_e32 v11, v13
	global_store_dwordx4 v[30:31], v[10:13], off offset:256 nt
	v_lshl_add_u64 v[14:15], v[16:17], 0, v[14:15]
	s_nop 0
	v_cvt_pk_bf16_f32 v10, v22, v23
	v_cvt_pk_bf16_f32 v11, v20, v21
	v_cvt_pk_bf16_f32 v12, v26, v27
	v_cvt_pk_bf16_f32 v13, v24, v25
	s_nop 0
	v_permlane16_swap_b32_e32 v10, v12
	v_permlane16_swap_b32_e32 v11, v13
	global_store_dwordx4 v[14:15], v[10:13], off nt
	s_nop 1
	v_cvt_pk_bf16_f32 v10, v4, v5
	v_cvt_pk_bf16_f32 v11, v2, v3
	v_cvt_pk_bf16_f32 v12, v8, v9
	v_cvt_pk_bf16_f32 v13, v6, v7
	s_nop 0
	v_permlane16_swap_b32_e32 v10, v12
	v_permlane16_swap_b32_e32 v11, v13
	global_store_dwordx4 v[14:15], v[10:13], off offset:256 nt
	s_branch .LBB0_108
